# latent Hyena K loop: counted lgkmcnt waits, each shared B fragment waited for at its first MFMA
# speedup vs baseline: 1.0049x; 1.0049x over previous
; DI void hyena_item_lat(const Params& p, int l, int it) {
;     ...
;   for (int sb = 0; sb < L; sb += 128) {
; #pragma unroll
;     for (int u = 0; u < 4; ++u) {
;       const int s0 = sb + 32 * u;
;       HY_LOADA(a[(0 - 2 * u) & 7], nb + s0)
;       HY_LOADA(a[(1 - 2 * u) & 7], nb - 16 + s0)
;       const bf16x8 bfrag = *(const bf16x8*)(ub + s0);
; #pragma unroll
;       for (int i = 0; i < 8; ++i) acc[i] = __builtin_amdgcn_mfma_f32_16x16x32_bf16(a[(i - 2 * u) & 7].v, bfrag, acc[i], 0, 0, 0);
;     }
;   }
;     ...
;   float ssq = 0.f;
;   for (int t = 0; t < 32; ++t) ssq += WSP(const float, OFF_PART)[(size_t)(f * 32 + t) * 256 + c];
;   const float scale = rsqrtf(ssq + EPSF);
;   const float bias = p.in[I_HYBIAS][l * 256 + c];
.LBB0_1139:
	s_waitcnt vmcnt(0)
	ds_write_b128 v94, v[82:85]
	s_waitcnt lgkmcnt(0)
	s_barrier
	ds_read_b128 v[66:69], v95
	ds_read_b128 v[70:73], v95 offset:1024
	ds_read_b128 v[86:89], v95 offset:2048
	ds_read_b128 v[74:77], v95 offset:3072
	v_xor_b32_e32 v94, 0x1000, v94
	v_xor_b32_e32 v95, 0x1000, v95
	s_mov_b64 s[38:39], 0x100
	s_waitcnt lgkmcnt(3)
	v_mfma_f32_16x16x32_bf16 v[4:7], v[48:51], v[66:69], v[4:7]
	v_add_u32_e32 v49, s13, v58
	v_add_u32_e32 v48, 0x880, v49
	v_add_u32_e32 v50, 0x870, v49
	v_mfma_f32_16x16x32_bf16 v[0:3], v[52:55], v[66:69], v[0:3]
	v_ashrrev_i32_e32 v49, 31, v48
	v_ashrrev_i32_e32 v51, 31, v50
	v_lshl_add_u64 v[78:79], v[48:49], 1, v[56:57]
	v_lshl_add_u64 v[80:81], v[50:51], 1, v[56:57]
	v_mfma_f32_16x16x32_bf16 v[12:15], v[32:35], v[66:69], v[12:15]
	global_load_dwordx4 v[48:51], v[78:79], off offset:64
	global_load_dwordx4 v[52:55], v[80:81], off offset:64
	s_addk_i32 s13, 0x80
	v_mfma_f32_16x16x32_bf16 v[8:11], v[36:39], v[66:69], v[8:11]
	s_cmpk_lt_u32 s13, 0x780
	s_waitcnt lgkmcnt(2)
	v_mfma_f32_16x16x32_bf16 v[4:7], v[32:35], v[70:73], v[4:7]
	global_load_dwordx4 v[32:35], v[78:79], off
	v_mfma_f32_16x16x32_bf16 v[0:3], v[36:39], v[70:73], v[0:3]
	global_load_dwordx4 v[36:39], v[80:81], off
	v_mfma_f32_16x16x32_bf16 v[20:23], v[40:43], v[66:69], v[20:23]
	v_mfma_f32_16x16x32_bf16 v[16:19], v[44:47], v[66:69], v[16:19]
	s_waitcnt vmcnt(1)
	v_mfma_f32_16x16x32_bf16 v[28:31], v[32:35], v[66:69], v[28:31]
	s_waitcnt vmcnt(0)
	v_mfma_f32_16x16x32_bf16 v[24:27], v[36:39], v[66:69], v[24:27]
	global_load_dwordx4 v[82:85], v[90:91], off offset:64
	v_lshl_add_u64 v[90:91], v[90:91], 0, s[38:39]
	v_lshl_add_u64 v[60:61], v[60:61], 0, s[38:39]
	v_mfma_f32_16x16x32_bf16 v[12:15], v[40:43], v[70:73], v[12:15]
	v_mfma_f32_16x16x32_bf16 v[8:11], v[44:47], v[70:73], v[8:11]
	v_mfma_f32_16x16x32_bf16 v[20:23], v[32:35], v[70:73], v[20:23]
	v_mfma_f32_16x16x32_bf16 v[16:19], v[36:39], v[70:73], v[16:19]
	v_mfma_f32_16x16x32_bf16 v[28:31], v[48:51], v[70:73], v[28:31]
	v_mfma_f32_16x16x32_bf16 v[24:27], v[52:55], v[70:73], v[24:27]
	s_waitcnt lgkmcnt(1)
	v_mfma_f32_16x16x32_bf16 v[4:7], v[40:43], v[86:89], v[4:7]
	global_load_dwordx4 v[40:43], v[78:79], off offset:192
	v_mfma_f32_16x16x32_bf16 v[0:3], v[44:47], v[86:89], v[0:3]
	global_load_dwordx4 v[44:47], v[80:81], off offset:192
	v_mfma_f32_16x16x32_bf16 v[12:15], v[32:35], v[86:89], v[12:15]
	v_mfma_f32_16x16x32_bf16 v[8:11], v[36:39], v[86:89], v[8:11]
	s_waitcnt lgkmcnt(0)
	v_mfma_f32_16x16x32_bf16 v[4:7], v[32:35], v[74:77], v[4:7]
	global_load_dwordx4 v[32:35], v[78:79], off offset:128
	v_mfma_f32_16x16x32_bf16 v[0:3], v[36:39], v[74:77], v[0:3]
	global_load_dwordx4 v[36:39], v[80:81], off offset:128
	v_mfma_f32_16x16x32_bf16 v[20:23], v[48:51], v[86:89], v[20:23]
	v_mfma_f32_16x16x32_bf16 v[16:19], v[52:55], v[86:89], v[16:19]
	v_mfma_f32_16x16x32_bf16 v[12:15], v[48:51], v[74:77], v[12:15]
	v_mfma_f32_16x16x32_bf16 v[8:11], v[52:55], v[74:77], v[8:11]
	s_waitcnt vmcnt(1)
	v_mfma_f32_16x16x32_bf16 v[28:31], v[32:35], v[86:89], v[28:31]
	s_waitcnt vmcnt(0)
	v_mfma_f32_16x16x32_bf16 v[24:27], v[36:39], v[86:89], v[24:27]
	v_mfma_f32_16x16x32_bf16 v[20:23], v[32:35], v[74:77], v[20:23]
	v_mfma_f32_16x16x32_bf16 v[16:19], v[36:39], v[74:77], v[16:19]
	v_mfma_f32_16x16x32_bf16 v[28:31], v[40:43], v[74:77], v[28:31]
	v_mfma_f32_16x16x32_bf16 v[24:27], v[44:47], v[74:77], v[24:27]
	s_cbranch_scc1 .LBB0_1139
	s_waitcnt vmcnt(0)
	v_mov_b64_e32 v[32:33], s[96:97]
	v_mad_i64_i32 v[32:33], s[38:39], v59, s9, v[32:33]
	s_mov_b64 s[38:39], 0x15600200
	s_ashr_i32 s35, s34, 31
	v_lshl_add_u64 v[32:33], v[32:33], 0, s[38:39]
	s_lshl_b64 s[38:39], s[34:35], 2
	s_add_u32 s38, s43, s38
	s_addc_u32 s39, s44, s39
	global_load_dword v38, v173, s[38:39]
	global_load_dword v39, v173, s[38:39] offset:1024
	global_load_dword v40, v173, s[38:39] offset:2048
	global_load_dword v41, v173, s[38:39] offset:3072
	v_mov_b32_e32 v92, 0x1000
	global_load_dword v42, v92, s[38:39]
	global_load_dword v43, v92, s[38:39] offset:1024
	global_load_dword v44, v92, s[38:39] offset:2048
	global_load_dword v45, v92, s[38:39] offset:3072
	v_mov_b32_e32 v92, 0x2000
	global_load_dword v46, v92, s[38:39]
	global_load_dword v47, v92, s[38:39] offset:1024
	global_load_dword v48, v92, s[38:39] offset:2048
	global_load_dword v49, v92, s[38:39] offset:3072
	v_mov_b32_e32 v92, 0x3000
	global_load_dword v50, v92, s[38:39]
	global_load_dword v51, v92, s[38:39] offset:1024
	global_load_dword v52, v92, s[38:39] offset:2048
	global_load_dword v53, v92, s[38:39] offset:3072
	v_mov_b32_e32 v92, 0x4000
	global_load_dword v54, v92, s[38:39]
	global_load_dword v55, v92, s[38:39] offset:1024
	global_load_dword v56, v92, s[38:39] offset:2048
	global_load_dword v57, v92, s[38:39] offset:3072
	v_mov_b32_e32 v92, 0x5000
	global_load_dword v58, v92, s[38:39]
	global_load_dword v65, v92, s[38:39] offset:1024
	global_load_dword v66, v92, s[38:39] offset:2048
	global_load_dword v67, v92, s[38:39] offset:3072
	v_mov_b32_e32 v92, 0x6000
	global_load_dword v68, v92, s[38:39]
	global_load_dword v69, v92, s[38:39] offset:1024
	global_load_dword v70, v92, s[38:39] offset:2048
	global_load_dword v71, v92, s[38:39] offset:3072
	v_mov_b32_e32 v92, 0x7000
	global_load_dword v72, v92, s[38:39]
	global_load_dword v73, v92, s[38:39] offset:1024
	global_load_dword v74, v92, s[38:39] offset:2048
	global_load_dword v75, v92, s[38:39] offset:3072
	v_readlane_b32 s16, v254, 29
	s_lshl_b64 s[36:37], s[36:37], 2
	v_readlane_b32 s18, v254, 31
	v_readlane_b32 s19, v254, 32
	s_add_u32 s36, s18, s36
	s_addc_u32 s37, s19, s37
	global_load_dword v37, v173, s[36:37]
; DI u16 f2bf(float x) { u32 u = __float_as_uint(x); u += 0x7fffu + ((u >> 16) & 1u); return (u16)(u >> 16); }
; DI float bf2f(u16 v) { return __uint_as_float(((u32)v) << 16); }
; DI void hyena_item_lat(const Params& p, int l, int it) {
;     ...
;   float ssq = 0.f;
;   for (int t = 0; t < 32; ++t) ssq += WSP(const float, OFF_PART)[(size_t)(f * 32 + t) * 256 + c];
;   const float scale = rsqrtf(ssq + EPSF);
;   const float bias = p.in[I_HYBIAS][l * 256 + c];
;   const u16* X1C = WSP(const u16, OFF_X1C);
;   u16* YM = WSP(u16, OFF_ACT);
;   const int b = l16;
; #pragma unroll
;   for (int i = 0; i < 8; ++i)
; #pragma unroll
;     for (int r = 0; r < 4; ++r) {
;       const int t = tt0 + 16 * i + kg * 4 + r;
;       const size_t row = (size_t)b * TPB + posoff + t;
;       const float uu = bf2f(UT[((size_t)(c * 16 + b)) * TPB + posoff + t]);
;       const float x1 = bf2f(X1C[row * 256 + c]);
;       YM[row * 1024 + c] = f2bf(x1 * (scale * acc[i][r] + bias * uu));
;     }
	s_movk_i32 s13, 0x900
	v_lshl_or_b32 v34, v64, 2, v63
	v_mov_b32_e32 v35, 0x100
	v_mad_u32_u24 v172, v62, s13, v35
	v_mov_b32_e32 v35, 0
	v_lshl_add_u64 v[94:95], v[34:35], 1, v[32:33]
	global_load_dwordx2 v[76:77], v[94:95], off
	global_load_dwordx2 v[78:79], v[94:95], off offset:32
	global_load_dwordx2 v[80:81], v[94:95], off offset:64
	global_load_dwordx2 v[82:83], v[94:95], off offset:96
	global_load_dwordx2 v[84:85], v[94:95], off offset:128
	global_load_dwordx2 v[86:87], v[94:95], off offset:160
	global_load_dwordx2 v[88:89], v[94:95], off offset:192
	global_load_dwordx2 v[90:91], v[94:95], off offset:224
	v_readlane_b32 s17, v254, 30
	s_lshl_b64 s[34:35], s[34:35], 1
	v_readlane_b32 s16, v255, 42
	v_readlane_b32 s17, v255, 43
	v_readlane_b32 s20, v254, 33
	v_readlane_b32 s21, v254, 34
	v_readlane_b32 s24, v254, 37
	v_readlane_b32 s18, v254, 10
	s_mov_b64 s[20:21], s[46:47]
	s_mov_b32 s24, s64
	v_readlane_b32 s22, v254, 35
	v_readlane_b32 s23, v254, 36
	v_readlane_b32 s25, v254, 38
	v_readlane_b32 s26, v254, 39
	v_readlane_b32 s27, v254, 40
	v_readlane_b32 s28, v254, 41
	v_readlane_b32 s29, v254, 42
	v_readlane_b32 s30, v254, 43
	v_readlane_b32 s31, v254, 44
	v_readlane_b32 s19, v254, 11
	s_add_u32 s38, s16, s34
	s_addc_u32 s39, s17, s35
	s_add_u32 s36, s6, s34
	s_addc_u32 s37, s7, s35
	v_lshlrev_b32_e32 v142, 13, v62
	v_lshl_add_u32 v142, v34, 2, v142
	s_waitcnt vmcnt(0)
	v_add_f32_e32 v36, 0, v38
	v_add_f32_e32 v36, v36, v39
	v_add_f32_e32 v36, v36, v40
	v_add_f32_e32 v36, v36, v41
	v_add_f32_e32 v36, v36, v42
	v_add_f32_e32 v36, v36, v43
	v_add_f32_e32 v36, v36, v44
	v_add_f32_e32 v36, v36, v45
	v_add_f32_e32 v36, v36, v46
	v_add_f32_e32 v36, v36, v47
	v_add_f32_e32 v36, v36, v48
	v_add_f32_e32 v36, v36, v49
	v_add_f32_e32 v36, v36, v50
	v_add_f32_e32 v36, v36, v51
	v_add_f32_e32 v36, v36, v52
	v_add_f32_e32 v36, v36, v53
	v_add_f32_e32 v36, v36, v54
	v_add_f32_e32 v36, v36, v55
	v_add_f32_e32 v36, v36, v56
	v_add_f32_e32 v36, v36, v57
	v_add_f32_e32 v36, v36, v58
	v_add_f32_e32 v36, v36, v65
	v_add_f32_e32 v36, v36, v66
	v_add_f32_e32 v36, v36, v67
	v_add_f32_e32 v36, v36, v68
	v_add_f32_e32 v36, v36, v69
	v_add_f32_e32 v36, v36, v70
	v_add_f32_e32 v36, v36, v71
	v_add_f32_e32 v36, v36, v72
	v_add_f32_e32 v36, v36, v73
	v_add_f32_e32 v36, v36, v74
	v_add_f32_e32 v36, v36, v75
	s_mov_b32 s13, 0x800000
	v_add_f32_e32 v36, 0x358637bd, v36
	v_cmp_gt_f32_e32 vcc, s13, v36
	v_mul_f32_e32 v35, 0x4b800000, v36
	s_movk_i32 s13, 0x900
	s_nop 0
	v_cndmask_b32_e32 v36, v36, v35, vcc
	v_rsq_f32_e32 v36, v36
	s_nop 0
	v_mul_f32_e32 v35, 0x45800000, v36
	v_cndmask_b32_e32 v36, v36, v35, vcc
	v_lshlrev_b32_e32 v92, 16, v76
	v_mul_f32_e32 v92, v37, v92
	v_fmac_f32_e32 v92, v28, v36
	v_mov_b32_e32 v28, v92
	v_and_b32_e32 v92, 0xffff0000, v76
	v_mul_f32_e32 v92, v37, v92
	v_fmac_f32_e32 v92, v29, v36
	v_mov_b32_e32 v29, v92
	v_lshlrev_b32_e32 v92, 16, v77
	v_mul_f32_e32 v92, v37, v92
	v_fmac_f32_e32 v92, v30, v36
	v_mov_b32_e32 v30, v92
	v_and_b32_e32 v92, 0xffff0000, v77
	v_mul_f32_e32 v92, v37, v92
	v_fmac_f32_e32 v92, v31, v36
	v_mov_b32_e32 v31, v92
	v_lshlrev_b32_e32 v92, 16, v78
	v_mul_f32_e32 v92, v37, v92
	v_fmac_f32_e32 v92, v24, v36
	v_mov_b32_e32 v24, v92
	v_and_b32_e32 v92, 0xffff0000, v78
	v_mul_f32_e32 v92, v37, v92
	v_fmac_f32_e32 v92, v25, v36
	v_mov_b32_e32 v25, v92
	v_lshlrev_b32_e32 v92, 16, v79
	v_mul_f32_e32 v92, v37, v92
	v_fmac_f32_e32 v92, v26, v36
	v_mov_b32_e32 v26, v92
	v_and_b32_e32 v92, 0xffff0000, v79
	v_mul_f32_e32 v92, v37, v92
	v_fmac_f32_e32 v92, v27, v36
	v_mov_b32_e32 v27, v92
	v_lshlrev_b32_e32 v92, 16, v80
	v_mul_f32_e32 v92, v37, v92
	v_fmac_f32_e32 v92, v20, v36
	v_mov_b32_e32 v20, v92
	v_and_b32_e32 v92, 0xffff0000, v80
	v_mul_f32_e32 v92, v37, v92
	v_fmac_f32_e32 v92, v21, v36
	v_mov_b32_e32 v21, v92
	v_lshlrev_b32_e32 v92, 16, v81
	v_mul_f32_e32 v92, v37, v92
	v_fmac_f32_e32 v92, v22, v36
	v_mov_b32_e32 v22, v92
	v_and_b32_e32 v92, 0xffff0000, v81
	v_mul_f32_e32 v92, v37, v92
	v_fmac_f32_e32 v92, v23, v36
	v_mov_b32_e32 v23, v92
	v_lshlrev_b32_e32 v92, 16, v82
	v_mul_f32_e32 v92, v37, v92
	v_fmac_f32_e32 v92, v16, v36
	v_mov_b32_e32 v16, v92
	v_and_b32_e32 v92, 0xffff0000, v82
	v_mul_f32_e32 v92, v37, v92
	v_fmac_f32_e32 v92, v17, v36
	v_mov_b32_e32 v17, v92
	v_lshlrev_b32_e32 v92, 16, v83
	v_mul_f32_e32 v92, v37, v92
	v_fmac_f32_e32 v92, v18, v36
	v_mov_b32_e32 v18, v92
	v_and_b32_e32 v92, 0xffff0000, v83
	v_mul_f32_e32 v92, v37, v92
	v_fmac_f32_e32 v92, v19, v36
	v_mov_b32_e32 v19, v92
	v_lshlrev_b32_e32 v92, 16, v84
	v_mul_f32_e32 v92, v37, v92
	v_fmac_f32_e32 v92, v12, v36
	v_mov_b32_e32 v12, v92
	v_and_b32_e32 v92, 0xffff0000, v84
	v_mul_f32_e32 v92, v37, v92
	v_fmac_f32_e32 v92, v13, v36
	v_mov_b32_e32 v13, v92
	v_lshlrev_b32_e32 v92, 16, v85
	v_mul_f32_e32 v92, v37, v92
	v_fmac_f32_e32 v92, v14, v36
	v_mov_b32_e32 v14, v92
	v_and_b32_e32 v92, 0xffff0000, v85
	v_mul_f32_e32 v92, v37, v92
	v_fmac_f32_e32 v92, v15, v36
	v_mov_b32_e32 v15, v92
	v_lshlrev_b32_e32 v92, 16, v86
	v_mul_f32_e32 v92, v37, v92
	v_fmac_f32_e32 v92, v8, v36
	v_mov_b32_e32 v8, v92
	v_and_b32_e32 v92, 0xffff0000, v86
	v_mul_f32_e32 v92, v37, v92
	v_fmac_f32_e32 v92, v9, v36
	v_mov_b32_e32 v9, v92
	v_lshlrev_b32_e32 v92, 16, v87
	v_mul_f32_e32 v92, v37, v92
	v_fmac_f32_e32 v92, v10, v36
	v_mov_b32_e32 v10, v92
	v_and_b32_e32 v92, 0xffff0000, v87
	v_mul_f32_e32 v92, v37, v92
	v_fmac_f32_e32 v92, v11, v36
	v_mov_b32_e32 v11, v92
	v_lshlrev_b32_e32 v92, 16, v88
	v_mul_f32_e32 v92, v37, v92
	v_fmac_f32_e32 v92, v4, v36
	v_mov_b32_e32 v4, v92
	v_and_b32_e32 v92, 0xffff0000, v88
	v_mul_f32_e32 v92, v37, v92
	v_fmac_f32_e32 v92, v5, v36
	v_mov_b32_e32 v5, v92
	v_lshlrev_b32_e32 v92, 16, v89
	v_mul_f32_e32 v92, v37, v92
	v_fmac_f32_e32 v92, v6, v36
	v_mov_b32_e32 v6, v92
	v_and_b32_e32 v92, 0xffff0000, v89
	v_mul_f32_e32 v92, v37, v92
	v_fmac_f32_e32 v92, v7, v36
	v_mov_b32_e32 v7, v92
	v_lshlrev_b32_e32 v92, 16, v90
	v_mul_f32_e32 v92, v37, v92
	v_fmac_f32_e32 v92, v0, v36
	v_mov_b32_e32 v0, v92
	v_and_b32_e32 v92, 0xffff0000, v90
	v_mul_f32_e32 v92, v37, v92
	v_fmac_f32_e32 v92, v1, v36
	v_mov_b32_e32 v1, v92
	v_lshlrev_b32_e32 v92, 16, v91
	v_mul_f32_e32 v92, v37, v92
	v_fmac_f32_e32 v92, v2, v36
	v_mov_b32_e32 v2, v92
	v_and_b32_e32 v92, 0xffff0000, v91
	v_mul_f32_e32 v92, v37, v92
	v_fmac_f32_e32 v92, v3, v36
	v_mov_b32_e32 v3, v92
	s_lshl_b32 s38, s34, 16
	s_add_u32 s38, s96, s38
	s_addc_u32 s39, s97, 0
	global_store_dwordx4 v142, v[28:31], s[38:39]
	global_store_dwordx4 v142, v[24:27], s[38:39] offset:64
	global_store_dwordx4 v142, v[20:23], s[38:39] offset:128
	global_store_dwordx4 v142, v[16:19], s[38:39] offset:192
	global_store_dwordx4 v142, v[12:15], s[38:39] offset:256
	global_store_dwordx4 v142, v[8:11], s[38:39] offset:320
	global_store_dwordx4 v142, v[4:7], s[38:39] offset:384
	global_store_dwordx4 v142, v[0:3], s[38:39] offset:448
